# attention unit: first K/V/K-rope tile loads issued right after the Q loads (before the rope math), dead address arithmetic removed from the exp section
# speedup vs baseline: 1.0004x; 1.0004x over previous
.LBB0_536:
	s_and_b64 vcc, exec, s[6:7]
	s_cbranch_vccz .LBB0_519
	s_ashr_i32 s53, s52, 5
	s_waitcnt vmcnt(14)
	v_mov_b32_e32 v2, v152
	s_sub_i32 s54, 15, s53
	s_lshl_b32 s71, s54, 8
	v_ashrrev_i32_e32 v0, 1, v2
	v_and_b32_e32 v102, 0xffffffe0, v0
	v_and_b32_e32 v116, 31, v2
	v_add_u32_e32 v103, s71, v102
	v_or_b32_e32 v104, v103, v116
	s_lshl_b32 s6, s52, 9
	s_and_b32 s14, s6, 0x3000
	v_ashrrev_i32_e32 v105, 31, v104
	v_lshl_add_u64 v[0:1], v[104:105], 0, s[14:15]
	s_waitcnt vmcnt(13)
	v_bfe_u32 v3, v2, 5, 1
	s_waitcnt vmcnt(11)
	v_lshlrev_b64 v[4:5], 6, v[0:1]
	s_waitcnt vmcnt(9)
	v_lshl_add_u64 v[6:7], s[24:25], 0, v[4:5]
	s_waitcnt vmcnt(8)
	v_lshlrev_b32_e32 v8, 5, v3
	s_waitcnt vmcnt(7)
	v_mov_b32_e32 v9, v101
	v_lshl_add_u64 v[4:5], s[26:27], 0, v[4:5]
	v_mov_b64_e32 v[20:21], s[42:43]
	s_waitcnt vmcnt(3)
	v_lshl_add_u64 v[12:13], v[6:7], 0, v[8:9]
	s_waitcnt vmcnt(0)
	v_lshl_add_u64 v[16:17], v[4:5], 0, v[8:9]
	s_and_b32 s72, s52, 7
	v_mad_u64_u32 v[20:21], s[6:7], v0, s66, v[20:21]
	global_load_dwordx4 v[4:7], v[16:17], off
	global_load_dwordx4 v[8:11], v[12:13], off
	s_nop 0
	global_load_dwordx4 v[12:15], v[12:13], off offset:16
	s_nop 0
	global_load_dwordx4 v[16:19], v[16:17], off offset:16
	v_mad_i32_i24 v21, v1, s66, v21
	s_mul_i32 s6, s72, 0xc0
	s_mov_b32 s7, s15
	v_lshl_add_u64 v[0:1], v[20:21], 0, s[6:7]
	v_lshlrev_b32_e32 v100, 4, v3
	v_lshl_add_u64 v[0:1], v[0:1], 0, v[100:101]
	global_load_dwordx4 v[20:23], v[0:1], off offset:128
	global_load_dwordx4 v[24:27], v[0:1], off offset:160
	global_load_dwordx4 v[64:67], v[0:1], off
	global_load_dwordx4 v[68:71], v[0:1], off offset:32
	global_load_dwordx4 v[72:75], v[0:1], off offset:64
	global_load_dwordx4 v[76:79], v[0:1], off offset:96
	s_lshl_b32 s10, s72, 8
	s_mov_b32 s11, s15
	v_cmp_gt_i32_e64 s[6:7], s67, v2
	v_ashrrev_i32_e32 v202, 3, v2
	v_ashrrev_i32_e32 v203, 31, v202
	v_lshl_add_u64 v[202:203], v[202:203], 0, s[14:15]
	v_lshlrev_b64 v[202:203], 11, v[202:203]
	v_lshl_add_u64 v[202:203], s[44:45], 0, v[202:203]
	v_lshl_add_u64 v[202:203], v[202:203], 0, s[10:11]
	v_lshlrev_b32_e32 v204, 3, v2
	v_and_b32_e32 v204, 56, v204
	v_lshlrev_b32_e32 v204, 1, v204
	v_mov_b32_e32 v205, v101
	v_lshl_add_u64 v[202:203], v[202:203], 0, v[204:205]
	global_load_dwordx4 v[88:91], v[202:203], off
	v_and_b32_e32 v160, 63, v2
	v_mov_b32_e32 v161, 0
	v_lshrrev_b32_e32 v162, 6, v2
	v_mov_b32_e32 v163, 0
	v_lshl_add_u64 v[166:167], v[160:161], 0, s[14:15]
	v_lshlrev_b64 v[166:167], 11, v[166:167]
	v_mul_u32_u24_e32 v159, 0x480, v162
	v_lshlrev_b32_e32 v162, 4, v162
	v_lshl_add_u64 v[164:165], s[44:45], 0, v[166:167]
	v_lshl_add_u64 v[164:165], v[164:165], 0, s[10:11]
	v_lshl_add_u64 v[164:165], v[164:165], 0, v[162:163]
	v_lshl_add_u32 v158, v160, 1, v159
	v_lshlrev_b64 v[166:167], 11, v[160:161]
	global_load_dwordx4 v[92:95], v[164:165], off offset:128
	s_and_saveexec_b64 s[8:9], s[6:7]
	v_bfe_u32 v206, v2, 2, 6
	v_or_b32_e32 v206, s14, v206
	v_lshlrev_b32_e32 v206, 6, v206
	v_mov_b32_e32 v207, v101
	v_lshl_add_u64 v[206:207], s[46:47], 0, v[206:207]
	v_lshlrev_b32_e32 v204, 3, v2
	v_and_b32_e32 v204, 24, v204
	v_lshlrev_b32_e32 v204, 1, v204
	v_lshl_add_u64 v[206:207], v[206:207], 0, v[204:205]
	global_load_dwordx4 v[96:99], v[206:207], off
	s_or_b64 exec, exec, s[8:9]
	s_waitcnt vmcnt(9)
	v_mov_b32_e32 v0, v4
	s_waitcnt vmcnt(8)
	v_mov_b32_e32 v1, v8
	v_mov_b32_e32 v28, v8
	v_mov_b32_e32 v29, v4
	v_mov_b32_e32 v8, v5
	s_waitcnt vmcnt(5)
	v_lshlrev_b32_e32 v39, 16, v20
	s_waitcnt vmcnt(4)
	v_lshlrev_b32_e32 v38, 16, v24
	v_mov_b32_e32 v30, v6
	v_mov_b32_e32 v31, v10
	v_mov_b32_e32 v32, v10
	v_mov_b32_e32 v33, v6
	v_mov_b32_e32 v10, v7
	v_mov_b32_e32 v6, v11
	v_mov_b32_e32 v34, v16
	v_mov_b32_e32 v35, v12
	v_mov_b32_e32 v36, v12
	v_mov_b32_e32 v12, v17
	v_and_b32_e32 v41, 0xffff0000, v20
	v_and_b32_e32 v40, 0xffff0000, v24
	v_lshlrev_b32_e32 v43, 16, v21
	v_lshlrev_b32_e32 v42, 16, v25
	v_and_b32_e32 v21, 0xffff0000, v21
	v_and_b32_e32 v20, 0xffff0000, v25
	v_lshlrev_b32_e32 v25, 16, v22
	v_lshlrev_b32_e32 v24, 16, v26
	v_and_b32_e32 v45, 0xffff0000, v22
	v_and_b32_e32 v44, 0xffff0000, v26
	v_pk_mul_f32 v[0:1], v[0:1], v[38:39]
	v_mov_b32_e32 v4, v9
	v_pk_mul_f32 v[28:29], v[28:29], v[38:39]
	v_pk_mul_f32 v[8:9], v[8:9], v[40:41]
	v_pk_mul_f32 v[10:11], v[10:11], v[20:21]
	v_pk_mul_f32 v[6:7], v[6:7], v[20:21]
	v_pk_mul_f32 v[20:21], v[34:35], v[24:25]
	v_pk_mul_f32 v[34:35], v[12:13], v[44:45]
	v_sub_f32_e32 v0, v1, v0
	v_mov_b32_e32 v37, v16
	v_pk_mul_f32 v[4:5], v[4:5], v[40:41]
	v_pk_mul_f32 v[30:31], v[30:31], v[42:43]
	v_pk_mul_f32 v[32:33], v[32:33], v[42:43]
	v_add_f32_e32 v1, v28, v29
	v_sub_f32_e32 v8, v9, v8
	v_cvt_pk_bf16_f32 v80, v0, v8
	v_sub_f32_e32 v0, v35, v34
	v_mov_b32_e32 v16, v13
	v_add_f32_e32 v4, v4, v5
	v_sub_f32_e32 v5, v31, v30
	v_add_f32_e32 v9, v32, v33
	v_sub_f32_e32 v10, v11, v10
	v_add_f32_e32 v6, v6, v7
	v_sub_f32_e32 v7, v21, v20
	v_cvt_pk_bf16_f32 v84, v1, v4
	v_cvt_pk_bf16_f32 v81, v5, v10
	v_cvt_pk_bf16_f32 v85, v9, v6
	v_cvt_pk_bf16_f32 v82, v7, v0
	v_pk_mul_f32 v[0:1], v[16:17], v[44:45]
	v_pk_mul_f32 v[24:25], v[36:37], v[24:25]
	v_add_f32_e32 v0, v0, v1
	v_add_f32_e32 v11, v24, v25
	v_cvt_pk_bf16_f32 v86, v11, v0
	v_lshlrev_b32_e32 v1, 16, v23
	v_lshlrev_b32_e32 v0, 16, v27
	v_mov_b32_e32 v4, v18
	v_mov_b32_e32 v5, v14
	v_pk_mul_f32 v[4:5], v[4:5], v[0:1]
	v_lshlrev_b32_e32 v10, 3, v2
	v_sub_f32_e32 v6, v5, v4
	v_mov_b32_e32 v4, v14
	v_mov_b32_e32 v5, v18
	v_pk_mul_f32 v[0:1], v[4:5], v[0:1]
	v_mov_b32_e32 v14, v19
	v_add_f32_e32 v7, v0, v1
	v_and_b32_e32 v1, 0xffff0000, v23
	v_and_b32_e32 v0, 0xffff0000, v27
	v_mov_b32_e32 v18, v15
	v_pk_mul_f32 v[4:5], v[14:15], v[0:1]
	v_pk_mul_f32 v[0:1], v[18:19], v[0:1]
	v_sub_f32_e32 v4, v5, v4
	v_add_f32_e32 v0, v0, v1
	v_cvt_pk_bf16_f32 v83, v6, v4
	v_cvt_pk_bf16_f32 v87, v7, v0
	v_ashrrev_i32_e32 v0, 3, v2
	v_ashrrev_i32_e32 v1, 31, v0
	v_lshl_add_u64 v[4:5], v[0:1], 0, s[14:15]
	v_lshlrev_b64 v[4:5], 11, v[4:5]
	v_lshl_add_u64 v[4:5], s[44:45], 0, v[4:5]
	v_lshl_add_u64 v[6:7], v[4:5], 0, s[10:11]
	v_and_b32_e32 v5, 56, v10
	v_lshlrev_b32_e32 v8, 1, v5
	v_mov_b32_e32 v9, v101
	v_lshl_add_u64 v[6:7], v[6:7], 0, v[8:9]
	v_bfe_u32 v4, v2, 2, 6
	v_and_b32_e32 v6, 24, v10
	s_and_saveexec_b64 s[8:9], s[6:7]
	s_cbranch_execz .LBB0_539
	v_or_b32_e32 v7, s14, v4
	v_lshlrev_b32_e32 v8, 6, v7
	v_mov_b32_e32 v9, v101
	v_lshl_add_u64 v[8:9], s[46:47], 0, v[8:9]
	v_lshlrev_b32_e32 v10, 1, v6
	v_mov_b32_e32 v11, v101
	v_lshl_add_u64 v[8:9], v[8:9], 0, v[10:11]

.LBB0_555:
	s_mul_i32 s10, s77, 0x2400
	v_add_u32_e32 v200, s10, v125
	v_add_u32_e32 v201, 0x7800, v200
	v_add_u32_e32 v200, 0x6800, v200
	ds_read2_b64 v[168:171], v200 offset1:2
	ds_read2_b64 v[172:175], v201 offset0:64 offset1:66
	ds_read2_b64 v[176:179], v200 offset0:4 offset1:6
	ds_read2_b64 v[180:183], v201 offset0:68 offset1:70
	ds_read2_b64 v[184:187], v200 offset0:8 offset1:10
	ds_read2_b64 v[188:191], v201 offset0:72 offset1:74
	ds_read2_b64 v[192:195], v200 offset0:12 offset1:14
	ds_read2_b64 v[196:199], v201 offset0:76 offset1:78
	v_fma_f32 v48, v48, s70, -v127
	v_fma_f32 v32, v32, s70, -v127
	v_exp_f32_e32 v48, v48
	v_exp_f32_e32 v133, v32
	v_fma_f32 v32, v49, s70, -v127
	v_fma_f32 v33, v33, s70, -v127
	v_exp_f32_e32 v32, v32
	v_exp_f32_e32 v134, v33
	v_fma_f32 v33, v50, s70, -v127
	v_fma_f32 v34, v34, s70, -v127
	v_exp_f32_e32 v33, v33
	v_exp_f32_e32 v50, v34
	v_add_f32_e32 v49, v48, v133
	v_add_f32_e32 v34, 0, v49
	v_add_f32_e32 v49, v32, v134
	v_fma_f32 v51, v51, s70, -v127
	v_fma_f32 v35, v35, s70, -v127
	v_add_f32_e32 v34, v49, v34
	v_add_f32_e32 v49, v33, v50
	v_exp_f32_e32 v51, v51
	v_exp_f32_e32 v135, v35
	v_fma_f32 v35, v52, s70, -v127
	v_fma_f32 v36, v36, s70, -v127
	v_exp_f32_e32 v35, v35
	v_exp_f32_e32 v52, v36
	v_add_f32_e32 v34, v49, v34
	v_fma_f32 v49, v53, s70, -v127
	v_fma_f32 v37, v37, s70, -v127
	v_exp_f32_e32 v49, v49
	v_exp_f32_e32 v53, v37
	v_fma_f32 v37, v54, s70, -v127
	v_fma_f32 v38, v38, s70, -v127
	v_exp_f32_e32 v37, v37
	v_exp_f32_e32 v54, v38
	v_fma_f32 v38, v55, s70, -v127
	v_fma_f32 v39, v39, s70, -v127
	v_add_f32_e32 v36, v51, v135
	v_exp_f32_e32 v38, v38
	v_exp_f32_e32 v55, v39
	v_add_f32_e32 v34, v36, v34
	v_add_f32_e32 v36, v35, v52
	v_add_f32_e32 v34, v36, v34
	v_add_f32_e32 v36, v49, v53
	v_add_f32_e32 v34, v36, v34
	v_add_f32_e32 v36, v37, v54
	v_add_f32_e32 v34, v36, v34
	v_add_f32_e32 v36, v38, v55
	v_add_f32_e32 v136, v36, v34
	v_fma_f32 v34, v57, s70, -v127
	v_fma_f32 v39, v56, s70, -v127
	v_exp_f32_e32 v57, v34
	v_fma_f32 v34, v58, s70, -v127
	v_cvt_pk_bf16_f32 v32, v48, v32
	v_exp_f32_e32 v56, v39
	v_fma_f32 v39, v40, s70, -v127
	v_exp_f32_e32 v58, v34
	v_cvt_pk_bf16_f32 v33, v33, v51
	v_cvt_pk_bf16_f32 v34, v35, v49
	v_exp_f32_e32 v40, v39
	v_cvt_pk_bf16_f32 v35, v37, v38
	s_waitcnt lgkmcnt(7)
	v_mfma_f32_32x32x16_bf16 v[0:15], v[32:35], v[168:171], v[0:15]
	v_fma_f32 v59, v59, s70, -v127
	v_exp_f32_e32 v51, v59
	v_fma_f32 v59, v60, s70, -v127
	v_fma_f32 v60, v61, s70, -v127
	v_fma_f32 v61, v62, s70, -v127
	v_fma_f32 v62, v63, s70, -v127
	v_exp_f32_e32 v59, v59
	v_exp_f32_e32 v60, v60
	v_exp_f32_e32 v61, v61
	v_exp_f32_e32 v62, v62
	s_waitcnt lgkmcnt(6)
	v_mfma_f32_32x32x16_bf16 v[16:31], v[32:35], v[172:175], v[16:31]
	v_cvt_pk_bf16_f32 v32, v56, v57
	v_cvt_pk_bf16_f32 v33, v58, v51
	v_cvt_pk_bf16_f32 v34, v59, v60
	v_cvt_pk_bf16_f32 v35, v61, v62
	v_fma_f32 v41, v41, s70, -v127
	v_fma_f32 v42, v42, s70, -v127
	s_waitcnt lgkmcnt(5)
	v_mfma_f32_32x32x16_bf16 v[0:15], v[32:35], v[176:179], v[0:15]
	v_fma_f32 v43, v43, s70, -v127
	v_fma_f32 v44, v44, s70, -v127
	v_fma_f32 v46, v46, s70, -v127
	v_fma_f32 v47, v47, s70, -v127
	v_exp_f32_e32 v41, v41
	v_exp_f32_e32 v42, v42
	s_waitcnt lgkmcnt(4)
	v_mfma_f32_32x32x16_bf16 v[16:31], v[32:35], v[180:183], v[16:31]
	v_cvt_pk_bf16_f32 v32, v133, v134
	v_cvt_pk_bf16_f32 v33, v50, v135
	v_cvt_pk_bf16_f32 v34, v52, v53
	v_cvt_pk_bf16_f32 v35, v54, v55
	v_exp_f32_e32 v43, v43
	v_exp_f32_e32 v44, v44
	s_waitcnt lgkmcnt(3)
	v_mfma_f32_32x32x16_bf16 v[0:15], v[32:35], v[184:187], v[0:15]
	v_fma_f32 v36, v45, s70, -v127
	v_exp_f32_e32 v45, v36
	v_exp_f32_e32 v46, v46
	v_exp_f32_e32 v47, v47
	v_add_f32_e32 v137, v56, v40
	v_add_f32_e32 v56, v137, v136
	s_waitcnt lgkmcnt(2)
	v_mfma_f32_32x32x16_bf16 v[16:31], v[32:35], v[188:191], v[16:31]
	v_cvt_pk_bf16_f32 v32, v40, v41
	v_cvt_pk_bf16_f32 v33, v42, v43
	v_cvt_pk_bf16_f32 v34, v44, v45
	v_cvt_pk_bf16_f32 v35, v46, v47
	v_add_f32_e32 v57, v57, v41
	v_add_f32_e32 v56, v57, v56
	s_waitcnt lgkmcnt(1)
	v_mfma_f32_32x32x16_bf16 v[0:15], v[32:35], v[192:195], v[0:15]
	v_add_f32_e32 v57, v58, v42
	v_add_f32_e32 v50, v57, v56
	v_add_f32_e32 v51, v51, v43
	v_add_f32_e32 v40, v51, v50
	v_add_f32_e32 v41, v59, v44
	v_add_f32_e32 v40, v41, v40
	s_waitcnt lgkmcnt(0)
	v_mfma_f32_32x32x16_bf16 v[16:31], v[32:35], v[196:199], v[16:31]
	v_add_f32_e32 v41, v60, v45
	v_add_f32_e32 v40, v41, v40
	v_add_f32_e32 v41, v61, v46
	v_add_f32_e32 v40, v41, v40
	v_add_f32_e32 v41, v62, v47
	v_add_f32_e32 v40, v41, v40
	v_fmac_f32_e32 v40, v126, v132
	v_mov_b32_e32 v132, v127
	v_mov_b32_e32 v126, v40
